# k13 + sc1 (write-through) on the P0 prologue's full-line dwordx2/x4 stores
# speedup vs baseline: 1.0544x; 1.0047x over previous
; __device__ __forceinline__ unsigned cvt_pk_bf16(float lo, float hi) { unsigned r; asm volatile("v_cvt_pk_bf16_f32 %0, %1, %2" : "=v"(r) : "v"(lo), "v"(hi)); return r; }
; #define LAS __attribute__((address_space(3)))
; __device__ __forceinline__ unsigned cvt_pk_bf16(float lo, float hi) { const f32x2 v = {lo, hi}; const bf16x2_t b = __builtin_convertvector(v, bf16x2_t); return __builtin_bit_cast(unsigned, b); }
; __device__ __forceinline__ void t_store(const TItem& t, const TRegs& r, LAS float* scr, int lane) {
;     const int nblk = t.N / 32, kb = t.item / nblk, nb = t.item % nblk, k0 = 64 * kb, n0 = 32 * nb;
;     const int rbase = (t.mode == 0) ? n0 : (((n0 >> 7) << 8) + (n0 & 127) + (t.mode == 2 ? 128 : 0));
; #pragma unroll
;     for (int i = 0; i < 8; ++i) { LAS float* d = scr + ((lane >> 3) + 8 * i) * 33 + 4 * (lane & 7); d[0] = r.v[i][0]; d[1] = r.v[i][1]; d[2] = r.v[i][2]; d[3] = r.v[i][3]; }
;     asm volatile("s_waitcnt lgkmcnt(0)" ::: "memory");
;     const int c = lane & 7;
; #pragma unroll
;     for (int j = 0; j < 4; ++j) { const int n = (lane >> 3) + 8 * j; const LAS float* s = scr + (8 * c) * 33 + n;
;         v4u o; o.x = cvt_pk_bf16(s[0 * 33], s[1 * 33]); o.y = cvt_pk_bf16(s[2 * 33], s[3 * 33]); o.z = cvt_pk_bf16(s[4 * 33], s[5 * 33]); o.w = cvt_pk_bf16(s[6 * 33], s[7 * 33]);
;         *(v4u*)(t.WT + (size_t)(rbase + n) * t.K + k0 + 8 * c) = o; }
;     asm volatile("s_waitcnt lgkmcnt(0)" ::: "memory");
; }
.LBB0_181:
	s_lshr_b32 s14, s14, 5
	v_cvt_f32_u32_e32 v128, s14
	s_sub_i32 s88, 0, s14
	s_abs_i32 s87, s4
	s_ashr_i32 s53, s4, 31
	v_rcp_iflag_f32_e32 v128, v128
	s_waitcnt vmcnt(31)
	ds_write2_b32 v140, v56, v57 offset1:1
	ds_write2_b32 v140, v58, v59 offset0:2 offset1:3
	v_add_u32_e32 v56, 0x420, v140
	s_waitcnt vmcnt(30)
	ds_write2_b32 v56, v16, v17 offset1:1
	v_mul_f32_e32 v128, 0x4f7ffffe, v128
	v_cvt_u32_f32_e32 v128, v128
	v_add_u32_e32 v16, 0x428, v140
	ds_write2_b32 v16, v18, v19 offset1:1
	v_add_u32_e32 v19, 0xc60, v140
	v_readfirstlane_b32 s89, v128
	s_mul_i32 s88, s88, s89
	s_mul_hi_u32 s88, s89, s88
	s_add_i32 s89, s89, s88
	s_mul_hi_u32 s88, s87, s89
	s_mul_i32 s89, s88, s14
	s_sub_i32 s87, s87, s89
	s_add_i32 s90, s88, 1
	s_sub_i32 s89, s87, s14
	s_cmp_ge_u32 s87, s14
	s_cselect_b32 s88, s90, s88
	s_cselect_b32 s87, s89, s87
	s_add_i32 s89, s88, 1
	s_cmp_ge_u32 s87, s14
	s_cselect_b32 s87, s89, s88
	s_xor_b32 s87, s87, s53
	s_sub_i32 s53, s87, s53
	s_mul_i32 s14, s53, s14
	s_sub_i32 s4, s4, s14
	s_lshl_b32 s14, s4, 5
	s_lshl_b32 s4, s4, 6
	s_and_b32 s4, s4, 0xffffff00
	s_and_b32 s87, s14, 0x60
	s_waitcnt vmcnt(28)
	ds_write2_b32 v19, v12, v13 offset1:1
	v_add_u32_e32 v12, 0xc68, v140
	s_cmp_eq_u32 s39, 2
	ds_write2_b32 v12, v14, v15 offset1:1
	v_add_u32_e32 v15, 0x14a0, v140
	s_cselect_b32 s88, 0x80, 0
	s_waitcnt vmcnt(26)
	ds_write2_b32 v15, v8, v9 offset1:1
	v_add_u32_e32 v9, 0x18c0, v140
	s_or_b32 s87, s87, s88
	s_waitcnt vmcnt(25)
	ds_write2_b32 v9, v4, v5 offset1:1
	v_add_u32_e32 v5, 0x1ce0, v140
	s_or_b32 s4, s87, s4
	v_add_u32_e32 v17, 0x840, v140
	v_add_u32_e32 v18, 0x848, v140
	v_add_u32_e32 v13, 0x1080, v140
	v_add_u32_e32 v14, 0x1088, v140
	v_add_u32_e32 v8, 0x14a8, v140
	v_add_u32_e32 v4, 0x18c8, v140
	s_waitcnt vmcnt(24)
	ds_write2_b32 v5, v0, v1 offset1:1
	v_add_u32_e32 v0, 0x1ce8, v140
	s_lshl_b32 s88, s53, 6
	ds_write2_b32 v17, v24, v25 offset1:1
	ds_write2_b32 v18, v26, v27 offset1:1
	ds_write2_b32 v13, v20, v21 offset1:1
	ds_write2_b32 v14, v22, v23 offset1:1
	ds_write2_b32 v8, v10, v11 offset1:1
	ds_write2_b32 v4, v6, v7 offset1:1
	ds_write2_b32 v0, v2, v3 offset1:1
	s_cmp_eq_u32 s39, 0
	s_cselect_b32 s4, s14, s4
	s_waitcnt lgkmcnt(0)
	ds_read2_b32 v[2:3], v139 offset0:33 offset1:41
	ds_read2_b32 v[6:7], v139 offset1:8
	ds_read2_b32 v[10:11], v139 offset0:66 offset1:74
	ds_read2_b32 v[24:25], v139 offset0:99 offset1:107
	ds_read2_b32 v[26:27], v139 offset0:132 offset1:140
	ds_read2_b32 v[58:59], v139 offset0:165 offset1:173
	ds_read2_b32 v[134:135], v139 offset0:198 offset1:206
	ds_read2_b32 v[142:143], v139 offset0:231 offset1:239
	v_or_b32_e32 v1, s4, v129
	s_ashr_i32 s14, s4, 31
	s_waitcnt lgkmcnt(6)
	v_cvt_pk_bf16_f32 v20, v6, v2
	v_mul_lo_u32 v2, s13, v1
	v_mad_u64_u32 v[144:145], s[90:91], s12, v1, 0
	s_mul_i32 s14, s12, s14
	s_ashr_i32 s89, s88, 31
	v_add3_u32 v145, v145, s14, v2
	v_lshl_add_u64 v[144:145], v[144:145], 1, s[6:7]
	s_lshl_b64 s[88:89], s[88:89], 1
	v_lshl_add_u64 v[144:145], v[144:145], 0, s[88:89]
	v_mov_b32_e32 v133, v131
	s_waitcnt lgkmcnt(4)
	v_cvt_pk_bf16_f32 v21, v10, v24
	s_waitcnt lgkmcnt(2)
	v_cvt_pk_bf16_f32 v22, v26, v58
	s_waitcnt lgkmcnt(0)
	v_cvt_pk_bf16_f32 v23, v134, v142
	v_lshl_add_u64 v[144:145], v[144:145], 0, v[132:133]
	v_or_b32_e32 v1, s4, v136
	global_store_dwordx4 v[144:145], v[20:23], off sc1
	v_mul_lo_u32 v6, s13, v1
	s_nop 0
	v_cvt_pk_bf16_f32 v20, v7, v3
	v_mad_u64_u32 v[2:3], s[90:91], s12, v1, 0
	v_add3_u32 v3, v3, s14, v6
	v_lshl_add_u64 v[2:3], v[2:3], 1, s[6:7]
	v_lshl_add_u64 v[2:3], v[2:3], 0, s[88:89]
	v_cvt_pk_bf16_f32 v21, v11, v25
	v_cvt_pk_bf16_f32 v22, v27, v59
	v_cvt_pk_bf16_f32 v23, v135, v143
	v_lshl_add_u64 v[2:3], v[2:3], 0, v[132:133]
	ds_read2_b32 v[6:7], v139 offset0:16 offset1:24
	ds_read2_b32 v[10:11], v139 offset0:49 offset1:57
	ds_read2_b32 v[24:25], v139 offset0:82 offset1:90
	ds_read2_b32 v[26:27], v139 offset0:115 offset1:123
	ds_read2_b32 v[58:59], v139 offset0:148 offset1:156
	ds_read2_b32 v[134:135], v139 offset0:181 offset1:189
	ds_read2_b32 v[142:143], v139 offset0:214 offset1:222
	ds_read2_b32 v[144:145], v139 offset0:247 offset1:255
	v_or_b32_e32 v1, s4, v137
	global_store_dwordx4 v[2:3], v[20:23], off sc1
	v_mad_u64_u32 v[2:3], s[90:91], s12, v1, 0
	s_waitcnt lgkmcnt(6)
	v_cvt_pk_bf16_f32 v20, v6, v10
	v_mul_lo_u32 v6, s13, v1
	v_add3_u32 v3, v3, s14, v6
	v_lshl_add_u64 v[2:3], v[2:3], 1, s[6:7]
	v_lshl_add_u64 v[2:3], v[2:3], 0, s[88:89]
	s_waitcnt lgkmcnt(4)
	v_cvt_pk_bf16_f32 v21, v24, v26
	s_waitcnt lgkmcnt(2)
	v_cvt_pk_bf16_f32 v22, v58, v134
	s_waitcnt lgkmcnt(0)
	v_cvt_pk_bf16_f32 v23, v142, v144
	v_lshl_add_u64 v[2:3], v[2:3], 0, v[132:133]
	v_or_b32_e32 v1, s4, v138
	global_store_dwordx4 v[2:3], v[20:23], off sc1
	v_mul_lo_u32 v6, s13, v1
	v_mad_u64_u32 v[2:3], s[12:13], s12, v1, 0
	v_add3_u32 v3, v3, s14, v6
	v_lshl_add_u64 v[2:3], v[2:3], 1, s[6:7]
	v_lshl_add_u64 v[2:3], v[2:3], 0, s[88:89]
	v_cvt_pk_bf16_f32 v20, v7, v11
	v_cvt_pk_bf16_f32 v21, v25, v27
	v_cvt_pk_bf16_f32 v22, v59, v135
	v_cvt_pk_bf16_f32 v23, v143, v145
	v_lshl_add_u64 v[2:3], v[2:3], 0, v[132:133]
	global_store_dwordx4 v[2:3], v[20:23], off sc1
	s_waitcnt lgkmcnt(0)
	s_add_i32 s4, s3, s5
	s_cmpk_gt_i32 s4, 0x28ff
	s_cbranch_scc1 .LBB0_106
; __device__ __forceinline__ unsigned cvt_pk_bf16(float lo, float hi) { unsigned r; asm volatile("v_cvt_pk_bf16_f32 %0, %1, %2" : "=v"(r) : "v"(lo), "v"(hi)); return r; }
; #define LAS __attribute__((address_space(3)))
; __device__ __forceinline__ unsigned cvt_pk_bf16(float lo, float hi) { const f32x2 v = {lo, hi}; const bf16x2_t b = __builtin_convertvector(v, bf16x2_t); return __builtin_bit_cast(unsigned, b); }
; __device__ __forceinline__ void t_store(const TItem& t, const TRegs& r, LAS float* scr, int lane) {
;     const int nblk = t.N / 32, kb = t.item / nblk, nb = t.item % nblk, k0 = 64 * kb, n0 = 32 * nb;
;     const int rbase = (t.mode == 0) ? n0 : (((n0 >> 7) << 8) + (n0 & 127) + (t.mode == 2 ? 128 : 0));
; #pragma unroll
;     for (int i = 0; i < 8; ++i) { LAS float* d = scr + ((lane >> 3) + 8 * i) * 33 + 4 * (lane & 7); d[0] = r.v[i][0]; d[1] = r.v[i][1]; d[2] = r.v[i][2]; d[3] = r.v[i][3]; }
;     asm volatile("s_waitcnt lgkmcnt(0)" ::: "memory");
;     const int c = lane & 7;
; #pragma unroll
;     for (int j = 0; j < 4; ++j) { const int n = (lane >> 3) + 8 * j; const LAS float* s = scr + (8 * c) * 33 + n;
;         v4u o; o.x = cvt_pk_bf16(s[0 * 33], s[1 * 33]); o.y = cvt_pk_bf16(s[2 * 33], s[3 * 33]); o.z = cvt_pk_bf16(s[4 * 33], s[5 * 33]); o.w = cvt_pk_bf16(s[6 * 33], s[7 * 33]);
;         *(v4u*)(t.WT + (size_t)(rbase + n) * t.K + k0 + 8 * c) = o; }
;     asm volatile("s_waitcnt lgkmcnt(0)" ::: "memory");
; }
	s_lshr_b32 s4, s20, 5
	v_cvt_f32_u32_e32 v1, s4
	s_sub_i32 s7, 0, s4
	s_abs_i32 s6, s33
	s_ashr_i32 s5, s33, 31
	v_rcp_iflag_f32_e32 v1, v1
	s_waitcnt vmcnt(27)
	ds_write2_b32 v140, v60, v61 offset1:1
	ds_write2_b32 v140, v62, v63 offset0:2 offset1:3
	s_waitcnt vmcnt(26)
	ds_write2_b32 v56, v28, v29 offset1:1
	ds_write2_b32 v16, v30, v31 offset1:1
	s_waitcnt vmcnt(25)
	ds_write2_b32 v17, v32, v33 offset1:1
	ds_write2_b32 v18, v34, v35 offset1:1
	s_waitcnt vmcnt(24)
	ds_write2_b32 v19, v36, v37 offset1:1
	ds_write2_b32 v12, v38, v39 offset1:1
	s_waitcnt vmcnt(23)
	ds_write2_b32 v13, v40, v41 offset1:1
	ds_write2_b32 v14, v42, v43 offset1:1
	s_waitcnt vmcnt(22)
	ds_write2_b32 v15, v44, v45 offset1:1
	ds_write2_b32 v8, v46, v47 offset1:1
	s_waitcnt vmcnt(21)
	ds_write2_b32 v9, v48, v49 offset1:1
	ds_write2_b32 v4, v50, v51 offset1:1
	s_waitcnt vmcnt(20)
	ds_write2_b32 v5, v52, v53 offset1:1
	ds_write2_b32 v0, v54, v55 offset1:1
	s_waitcnt lgkmcnt(0)
	v_mul_f32_e32 v1, 0x4f7ffffe, v1
	v_cvt_u32_f32_e32 v1, v1
	ds_read2_b32 v[4:5], v139 offset0:33 offset1:41
	ds_read2_b32 v[6:7], v139 offset1:8
	ds_read2_b32 v[8:9], v139 offset0:66 offset1:74
	ds_read2_b32 v[10:11], v139 offset0:99 offset1:107
	ds_read2_b32 v[12:13], v139 offset0:132 offset1:140
	ds_read2_b32 v[14:15], v139 offset0:165 offset1:173
	ds_read2_b32 v[16:17], v139 offset0:198 offset1:206
	ds_read2_b32 v[18:19], v139 offset0:231 offset1:239
	s_waitcnt lgkmcnt(6)
	v_cvt_pk_bf16_f32 v0, v6, v4
	s_waitcnt lgkmcnt(2)
	v_cvt_pk_bf16_f32 v2, v12, v14
	v_readfirstlane_b32 s12, v1
	s_mul_i32 s7, s7, s12
	s_mul_hi_u32 s7, s12, s7
	s_add_i32 s12, s12, s7
	s_mul_hi_u32 s7, s6, s12
	s_mul_i32 s12, s7, s4
	s_sub_i32 s6, s6, s12
	s_add_i32 s13, s7, 1
	s_sub_i32 s12, s6, s4
	s_cmp_ge_u32 s6, s4
	s_cselect_b32 s7, s13, s7
	s_cselect_b32 s6, s12, s6
	s_add_i32 s12, s7, 1
	s_cmp_ge_u32 s6, s4
	s_cselect_b32 s6, s12, s7
	s_xor_b32 s6, s6, s5
	s_sub_i32 s5, s6, s5
	s_mul_i32 s4, s5, s4
	s_sub_i32 s4, s33, s4
	s_lshl_b32 s6, s4, 5
	s_lshl_b32 s4, s4, 6
	s_and_b32 s4, s4, 0xffffff00
	s_and_b32 s7, s6, 0x60
	s_cmp_eq_u32 s52, 2
	s_cselect_b32 s12, 0x80, 0
	s_or_b32 s7, s7, s12
	s_or_b32 s7, s7, s4
	s_lshl_b32 s4, s5, 6
	s_cmp_eq_u32 s52, 0
	s_cselect_b32 s12, s6, s7
	v_or_b32_e32 v4, s12, v129
	v_mad_u64_u32 v[20:21], s[6:7], s18, v4, 0
	s_ashr_i32 s6, s12, 31
	v_mul_lo_u32 v6, s19, v4
	s_mul_i32 s13, s18, s6
	s_ashr_i32 s5, s4, 31
	v_add3_u32 v21, v21, s13, v6
	v_lshl_add_u64 v[20:21], v[20:21], 1, s[16:17]
	s_lshl_b64 s[4:5], s[4:5], 1
	v_lshl_add_u64 v[20:21], v[20:21], 0, s[4:5]
	v_cvt_pk_bf16_f32 v1, v8, v10
	s_waitcnt lgkmcnt(0)
	v_cvt_pk_bf16_f32 v3, v16, v18
	v_lshl_add_u64 v[20:21], v[20:21], 0, v[132:133]
	v_or_b32_e32 v4, s12, v136
	global_store_dwordx4 v[20:21], v[0:3], off sc1
	v_mul_lo_u32 v6, s19, v4
	s_nop 0
	v_cvt_pk_bf16_f32 v0, v7, v5
	v_mad_u64_u32 v[4:5], s[6:7], s18, v4, 0
	v_add3_u32 v5, v5, s13, v6
	v_lshl_add_u64 v[4:5], v[4:5], 1, s[16:17]
	v_lshl_add_u64 v[4:5], v[4:5], 0, s[4:5]
	v_cvt_pk_bf16_f32 v1, v9, v11
	v_cvt_pk_bf16_f32 v2, v13, v15
	v_cvt_pk_bf16_f32 v3, v17, v19
	v_lshl_add_u64 v[4:5], v[4:5], 0, v[132:133]
	ds_read2_b32 v[6:7], v139 offset0:16 offset1:24
	ds_read2_b32 v[8:9], v139 offset0:49 offset1:57
	ds_read2_b32 v[10:11], v139 offset0:82 offset1:90
	ds_read2_b32 v[12:13], v139 offset0:115 offset1:123
	ds_read2_b32 v[14:15], v139 offset0:148 offset1:156
	ds_read2_b32 v[16:17], v139 offset0:181 offset1:189
	ds_read2_b32 v[18:19], v139 offset0:214 offset1:222
	ds_read2_b32 v[20:21], v139 offset0:247 offset1:255
	global_store_dwordx4 v[4:5], v[0:3], off sc1
	v_or_b32_e32 v4, s12, v137
	s_waitcnt lgkmcnt(6)
	v_cvt_pk_bf16_f32 v0, v6, v8
	v_mul_lo_u32 v6, s19, v4
	v_mad_u64_u32 v[4:5], s[6:7], s18, v4, 0
	v_add3_u32 v5, v5, s13, v6
	v_lshl_add_u64 v[4:5], v[4:5], 1, s[16:17]
	v_lshl_add_u64 v[4:5], v[4:5], 0, s[4:5]
	s_waitcnt lgkmcnt(4)
	v_cvt_pk_bf16_f32 v1, v10, v12
	s_waitcnt lgkmcnt(2)
	v_cvt_pk_bf16_f32 v2, v14, v16
	s_waitcnt lgkmcnt(0)
	v_cvt_pk_bf16_f32 v3, v18, v20
	v_lshl_add_u64 v[4:5], v[4:5], 0, v[132:133]
	global_store_dwordx4 v[4:5], v[0:3], off sc1
	v_or_b32_e32 v4, s12, v138
	v_mul_lo_u32 v6, s19, v4
	v_mad_u64_u32 v[4:5], s[6:7], s18, v4, 0
	v_add3_u32 v5, v5, s13, v6
	v_lshl_add_u64 v[4:5], v[4:5], 1, s[16:17]
	v_lshl_add_u64 v[4:5], v[4:5], 0, s[4:5]
	v_cvt_pk_bf16_f32 v0, v7, v9
	v_cvt_pk_bf16_f32 v1, v11, v13
	v_cvt_pk_bf16_f32 v2, v15, v17
	v_cvt_pk_bf16_f32 v3, v19, v21
	v_lshl_add_u64 v[4:5], v[4:5], 0, v[132:133]
	global_store_dwordx4 v[4:5], v[0:3], off sc1
	s_waitcnt lgkmcnt(0)
	s_branch .LBB0_106

; __device__ __forceinline__ unsigned cvt_pk_bf16(float lo, float hi) { unsigned r; asm volatile("v_cvt_pk_bf16_f32 %0, %1, %2" : "=v"(r) : "v"(lo), "v"(hi)); return r; }
; __device__ __forceinline__ unsigned cvt_pk_bf16(float lo, float hi) { const f32x2 v = {lo, hi}; const bf16x2_t b = __builtin_convertvector(v, bf16x2_t); return __builtin_bit_cast(unsigned, b); }
; __device__ __forceinline__ void p0_prologue(Frame& F) {
;     ...
;     for (int m0 = gw; m0 < MT; m0 += 2 * NGW) {
;         f32x4 v[2][4], pv[2]; int mm[2];
; #pragma unroll
;         for (int q = 0; q < 2; ++q) {
;             const int m = (m0 + q * NGW < MT) ? m0 + q * NGW : m0; mm[q] = m;
;             const float* xrow = (m < MP) ? A.in[0] + (size_t)m * D : A.in[1] + (size_t)(m - MP) * D;
;             const float* prow = (m < MP) ? A.in[2] + (size_t)m * DPLE : A.in[3] + (size_t)(m - MP) * DPLE;
; #pragma unroll
;             for (int j = 0; j < 4; ++j) v[q][j] = *((const f32x4*)xrow + F.lane + 64 * j);
;             pv[q] = *((const f32x4*)prow + F.lane);
;         }
; #pragma unroll
;         for (int q = 0; q < 2; ++q) {
;             const int m = mm[q]; float s = 0.f;
; #pragma unroll
;             for (int j = 0; j < 4; ++j) s += (v[q][j][0] * v[q][j][0] + v[q][j][1] * v[q][j][1]) + (v[q][j][2] * v[q][j][2] + v[q][j][3] * v[q][j][3]);
;             s = wave_sum(s);
;             v2u* o8 = (v2u*)(XB + (size_t)m * D) + F.lane;
; #pragma unroll
;             for (int j = 0; j < 4; ++j) { v2u w; w.x = cvt_pk_bf16(v[q][j][0], v[q][j][1]); w.y = cvt_pk_bf16(v[q][j][2], v[q][j][3]); o8[64 * j] = w; }
;             if (F.lane < 16) SS[(size_t)m * 16 + F.lane] = (F.lane == 0) ? s : 0.f;
;             v2u w; w.x = cvt_pk_bf16(pv[q][0], pv[q][1]); w.y = cvt_pk_bf16(pv[q][2], pv[q][3]);
;             *((v2u*)(PE + (size_t)m * DPLE) + F.lane) = w;
;         }
.LBB0_185:
	s_or_b64 exec, exec, s[10:11]
	s_lshl_b64 s[10:11], s[12:13], 9
	s_waitcnt vmcnt(9)
	v_cvt_pk_bf16_f32 v0, v0, v1
	v_cvt_pk_bf16_f32 v1, v2, v3
	v_lshl_add_u64 v[2:3], v[28:29], 0, s[10:11]
	s_add_i32 s10, s4, s3
	s_cmpk_gt_i32 s10, 0x43ff
	global_store_dwordx2 v[2:3], v[0:1], off sc1
	s_cbranch_scc1 .LBB0_190
.LBB0_186:
	s_add_i32 s4, s10, 0xffffc000
	s_ashr_i32 s11, s10, 31
	s_cmpk_lt_i32 s10, 0x4000
	s_cselect_b32 s12, 0, 8
	s_cselect_b32 s5, s11, 0
	s_cselect_b32 s4, s10, s4
	s_cselect_b32 s16, 16, 24
	s_add_u32 s12, s0, s12
	s_addc_u32 s13, s1, 0
	s_load_dwordx2 s[12:13], s[12:13], 0x0
	s_lshl_b64 s[14:15], s[4:5], 12
	s_waitcnt lgkmcnt(0)
	s_add_u32 s12, s12, s14
	s_addc_u32 s13, s13, s15
	global_load_dwordx4 v[38:41], v36, s[12:13] nt
	global_load_dwordx4 v[42:45], v36, s[12:13] offset:1024 nt
	global_load_dwordx4 v[46:49], v36, s[12:13] offset:2048 nt
	global_load_dwordx4 v[50:53], v36, s[12:13] offset:3072 nt
	s_add_u32 s12, s0, s16
	s_addc_u32 s13, s1, 0
	s_load_dwordx2 s[12:13], s[12:13], 0x0
	s_lshl_b64 s[4:5], s[4:5], 10
	s_waitcnt lgkmcnt(0)
	s_add_u32 s14, s12, s4
	s_addc_u32 s15, s13, s5
	s_add_i32 s4, s10, s3
	s_cmpk_lt_i32 s4, 0x4400
	s_cselect_b32 s12, s4, s10
	s_ashr_i32 s13, s12, 31
	s_add_i32 s5, s12, 0xffffc000
	s_cmpk_lt_i32 s12, 0x4000
	s_cselect_b32 s16, s12, s5
	s_cselect_b32 s5, 0, 8
	s_cselect_b32 s17, s13, 0
	s_cselect_b32 s22, 16, 24
	s_add_u32 s18, s0, s5
	s_addc_u32 s19, s1, 0
	s_load_dwordx2 s[18:19], s[18:19], 0x0
	s_lshl_b64 s[20:21], s[16:17], 12
	s_waitcnt lgkmcnt(0)
	s_add_u32 s18, s18, s20
	s_addc_u32 s19, s19, s21
	s_add_u32 s20, s0, s22
	s_addc_u32 s21, s1, 0
	s_load_dwordx2 s[20:21], s[20:21], 0x0
	global_load_dwordx4 v[20:23], v36, s[14:15] nt
	global_load_dwordx4 v[16:19], v36, s[18:19] nt
	global_load_dwordx4 v[12:15], v36, s[18:19] offset:1024 nt
	global_load_dwordx4 v[4:7], v36, s[18:19] offset:2048 nt
	s_lshl_b64 s[14:15], s[16:17], 10
	s_waitcnt lgkmcnt(0)
	s_add_u32 s14, s20, s14
	s_addc_u32 s15, s21, s15
	global_load_dwordx4 v[8:11], v36, s[18:19] offset:3072 nt
	global_load_dwordx4 v[0:3], v36, s[14:15] nt
	s_lshl_b64 s[14:15], s[10:11], 11
	s_waitcnt vmcnt(9)
	v_mul_f32_e32 v37, v39, v39
	v_mul_f32_e32 v54, v41, v41
	s_waitcnt vmcnt(8)
	v_mul_f32_e32 v55, v43, v43
	v_mul_f32_e32 v56, v45, v45
	s_waitcnt vmcnt(7)
	v_mul_f32_e32 v57, v47, v47
	v_mul_f32_e32 v58, v49, v49
	v_fmac_f32_e32 v37, v38, v38
	v_fmac_f32_e32 v54, v40, v40
	v_fmac_f32_e32 v55, v42, v42
	v_fmac_f32_e32 v56, v44, v44
	s_waitcnt vmcnt(6)
	v_mul_f32_e32 v59, v51, v51
	v_mul_f32_e32 v60, v53, v53
	v_fmac_f32_e32 v57, v46, v46
	v_fmac_f32_e32 v58, v48, v48
	v_add_f32_e32 v37, v37, v54
	v_add_f32_e32 v54, v55, v56
	v_fmac_f32_e32 v59, v50, v50
	v_fmac_f32_e32 v60, v52, v52
	v_add_f32_e32 v55, v57, v58
	v_add_f32_e32 v37, v37, v54
	v_add_f32_e32 v56, v59, v60
	v_add_f32_e32 v37, v37, v55
	v_add_f32_e32 v37, v37, v56
	ds_bpermute_b32 v54, v30, v37
	v_cvt_pk_bf16_f32 v38, v38, v39
	v_cvt_pk_bf16_f32 v39, v40, v41
	v_cvt_pk_bf16_f32 v40, v42, v43
	v_cvt_pk_bf16_f32 v41, v44, v45
	s_waitcnt lgkmcnt(0)
	v_add_f32_e32 v37, v37, v54
	ds_bpermute_b32 v54, v31, v37
	v_cvt_pk_bf16_f32 v42, v46, v47
	s_waitcnt lgkmcnt(0)
	v_add_f32_e32 v37, v37, v54
	ds_bpermute_b32 v54, v32, v37
	s_waitcnt lgkmcnt(0)
	v_add_f32_e32 v37, v37, v54
	ds_bpermute_b32 v56, v33, v37
	v_lshl_add_u64 v[54:55], v[24:25], 0, s[14:15]
	global_store_dwordx2 v[54:55], v[38:39], off sc1
	global_store_dwordx2 v[54:55], v[40:41], off offset:512 sc1
	v_cvt_pk_bf16_f32 v40, v50, v51
	v_cvt_pk_bf16_f32 v41, v52, v53
	s_waitcnt lgkmcnt(0)
	v_add_f32_e32 v37, v37, v56
	ds_bpermute_b32 v43, v34, v37
	global_store_dwordx2 v[54:55], v[40:41], off offset:1536 sc1
	s_waitcnt lgkmcnt(0)
	v_add_f32_e32 v37, v37, v43
	ds_bpermute_b32 v38, v35, v37
	v_cvt_pk_bf16_f32 v43, v48, v49
	global_store_dwordx2 v[54:55], v[42:43], off offset:1024 sc1
	s_and_saveexec_b64 s[14:15], vcc
	s_cbranch_execz .LBB0_188
	s_waitcnt lgkmcnt(0)
	v_add_f32_e32 v37, v37, v38
	s_lshl_b64 s[16:17], s[10:11], 6
	v_lshl_add_u64 v[38:39], v[26:27], 0, s[16:17]
	v_cndmask_b32_e64 v37, 0, v37, s[6:7]
	global_store_dword v[38:39], v37, off
.LBB0_188:
	s_or_b64 exec, exec, s[14:15]
	s_waitcnt vmcnt(8)
	v_mul_f32_e32 v37, v17, v17
	s_waitcnt lgkmcnt(0)
	v_mul_f32_e32 v38, v19, v19
	v_fmac_f32_e32 v37, v16, v16
	v_fmac_f32_e32 v38, v18, v18
	v_add_f32_e32 v37, v37, v38
	s_waitcnt vmcnt(7)
	v_mul_f32_e32 v38, v13, v13
	v_mul_f32_e32 v39, v15, v15
	v_fmac_f32_e32 v38, v12, v12
	v_fmac_f32_e32 v39, v14, v14
	v_add_f32_e32 v38, v38, v39
	v_add_f32_e32 v37, v37, v38
	s_waitcnt vmcnt(6)
	v_mul_f32_e32 v38, v5, v5
	v_mul_f32_e32 v39, v7, v7
	v_fmac_f32_e32 v38, v4, v4
	v_fmac_f32_e32 v39, v6, v6
	v_add_f32_e32 v38, v38, v39
	v_add_f32_e32 v37, v37, v38
	s_waitcnt vmcnt(5)
	v_mul_f32_e32 v38, v9, v9
	v_mul_f32_e32 v39, v11, v11
	v_fmac_f32_e32 v38, v8, v8
	v_fmac_f32_e32 v39, v10, v10
	v_add_f32_e32 v38, v38, v39
	v_add_f32_e32 v37, v37, v38
	ds_bpermute_b32 v38, v30, v37
	s_lshl_b64 s[10:11], s[10:11], 9
	v_cvt_pk_bf16_f32 v20, v20, v21
	v_cvt_pk_bf16_f32 v21, v22, v23
	v_lshl_add_u64 v[22:23], v[28:29], 0, s[10:11]
	s_waitcnt lgkmcnt(0)
	v_add_f32_e32 v37, v37, v38
	ds_bpermute_b32 v38, v31, v37
	global_store_dwordx2 v[22:23], v[20:21], off sc1
	s_lshl_b64 s[10:11], s[12:13], 11
	v_lshl_add_u64 v[22:23], v[24:25], 0, s[10:11]
	v_cvt_pk_bf16_f32 v4, v4, v5
	s_waitcnt lgkmcnt(0)
	v_add_f32_e32 v37, v37, v38
	ds_bpermute_b32 v38, v32, v37
	v_cvt_pk_bf16_f32 v5, v6, v7
	v_cvt_pk_bf16_f32 v16, v16, v17
	v_cvt_pk_bf16_f32 v17, v18, v19
	v_cvt_pk_bf16_f32 v12, v12, v13
	s_waitcnt lgkmcnt(0)
	v_add_f32_e32 v37, v37, v38
	ds_bpermute_b32 v38, v33, v37
	v_cvt_pk_bf16_f32 v13, v14, v15
	global_store_dwordx2 v[22:23], v[4:5], off offset:1024 sc1
	v_cvt_pk_bf16_f32 v4, v8, v9
	v_cvt_pk_bf16_f32 v5, v10, v11
	s_waitcnt lgkmcnt(0)
	v_add_f32_e32 v37, v37, v38
	ds_bpermute_b32 v38, v34, v37
	global_store_dwordx2 v[22:23], v[16:17], off sc1
	global_store_dwordx2 v[22:23], v[12:13], off offset:512 sc1
	global_store_dwordx2 v[22:23], v[4:5], off offset:1536 sc1
	s_waitcnt lgkmcnt(0)
	v_add_f32_e32 v20, v37, v38
	ds_bpermute_b32 v21, v35, v20
	s_and_saveexec_b64 s[10:11], vcc
	s_cbranch_execz .LBB0_185
	s_waitcnt lgkmcnt(0)
	v_add_f32_e32 v6, v20, v21
	s_lshl_b64 s[14:15], s[12:13], 6
	v_lshl_add_u64 v[4:5], v[26:27], 0, s[14:15]
	v_cndmask_b32_e64 v6, 0, v6, s[6:7]
	global_store_dword v[4:5], v6, off
	s_branch .LBB0_185

; __device__ __forceinline__ void p0_prologue(Frame& F) {
;     ...
;     for (int e = blockIdx.x * (NWAVES * 64) + F.tid; e < ROPE_ROWS * 32; e += F.G * NWAVES * 64) {
;         const int pr = e >> 5, i = e & 31; const int pos = pr < 2048 ? pr : PAST + (pr - 2048);
;         const double inv = (double)exp2f(-(float)i * (13.287712379549449f / 32.0f));
;         double t = (double)pos * inv * 0.15915494309189535; t -= floor(t);
;         const float f = (float)t;
;         rope[e] = (f32x2){__builtin_amdgcn_cosf(f), __builtin_amdgcn_sinf(f)};
;     }
.LBB0_195:
	v_ashrrev_i32_e32 v1, 5, v0
	v_add_u32_e32 v6, 0x3800, v1
	v_cmp_gt_i32_e32 vcc, s3, v1
	v_add_u32_e32 v0, s10, v0
	s_nop 0
	v_cndmask_b32_e32 v1, v6, v1, vcc
	v_cvt_f64_i32_e32 v[6:7], v1
	v_mul_f64 v[6:7], v[6:7], v[2:3]
	v_mul_f64 v[8:9], v[6:7], s[16:17]
	v_floor_f64_e32 v[8:9], v[8:9]
	v_fma_f64 v[6:7], v[6:7], s[16:17], -v[8:9]
	v_cvt_f32_f64_e32 v1, v[6:7]
	v_cos_f32_e32 v6, v1
	v_sin_f32_e32 v7, v1
	v_cmp_lt_i32_e32 vcc, s4, v0
	s_or_b64 s[14:15], vcc, s[14:15]
	global_store_dwordx2 v[4:5], v[6:7], off sc1
	v_lshl_add_u64 v[4:5], v[4:5], 0, s[12:13]
	s_andn2_b64 exec, exec, s[14:15]
	s_cbranch_execnz .LBB0_195
